# v5
# speedup vs baseline: 1.0092x; 1.0092x over previous
; __device__ __forceinline__ uint4 ldg16(const void* p) { const u32x4 v = *(const __attribute__((address_space(1))) u32x4*)(p); return make_uint4(v.x, v.y, v.z, v.w); }
; __device__ __forceinline__ void attn_phase(const Params& p, char* shmc, int tid, int wv) {
;     ...
;   for (int tile = blockIdx.x; tile < 4096; tile += gridDim.x) {
;     const int h = tile & 15, qb = 255 - (tile >> 4);
;     {
;       const int row = tid >> 3, c0 = (tid & 7) * 16;
;       const u16* src = QKV + ((long)qb * 64 + row) * 6144 + h * 128 + c0;
;       *(uint4*)&Qs[row * 136 + c0] = ldg16(src);
;       *(uint4*)&Qs[row * 136 + c0 + 8] = ldg16(src + 8);
;     }
;     float carry = 0.f;
;     f32x4 oacc[4];
; #pragma unroll
;     for (int i = 0; i < 4; ++i) oacc[i] = f32x4{0.f, 0.f, 0.f, 0.f};
;     const int krow = tid >> 3, kc0 = (tid & 7) * 16, vkey = tid & 63, vd0 = wv * 16;
;     uint4 ka, kb4, va, vb;
;     {
;       const u16* src = QKV + ((long)qb * 64 + krow) * 6144 + 2048 + h * 128 + kc0;
;       ka = ldg16(src); kb4 = ldg16(src + 8);
;       const u16* vs = QKV + ((long)qb * 64 + vkey) * 6144 + 4096 + h * 128 + vd0;
;       va = ldg16(vs); vb = ldg16(vs + 8);
;     }
;     ...
;         const int kn = kb > 0 ? kb - 1 : 0;
;         const u16* src = QKV + ((long)kn * 64 + krow) * 6144 + 2048 + h * 128 + kc0;
;         ka = ldg16(src); kb4 = ldg16(src + 8);
;         const u16* vs = QKV + ((long)kn * 64 + vkey) * 6144 + 4096 + h * 128 + vd0;
;         va = ldg16(vs); vb = ldg16(vs + 8);
.LBB0_308:
	s_ashr_i32 s18, s7, 4
	s_sub_i32 s88, 0xff, s18
	s_lshl_b64 s[48:49], s[88:89], 6
	v_lshl_add_u64 v[0:1], s[48:49], 0, v[44:45]
	v_mad_u64_u32 v[2:3], s[14:15], v0, s71, v[40:41]
	s_lshl_b32 s14, s7, 7
	s_and_b32 s59, s14, 0x780
	v_mad_i32_i24 v3, v1, s71, v3
	s_lshl_b32 s14, s59, 1
	s_mov_b32 s15, s89
	v_lshl_add_u64 v[0:1], v[2:3], 0, s[14:15]
	v_mov_b32_e32 v57, v213
	v_lshl_add_u64 v[8:9], v[0:1], 0, v[56:57]
	global_load_dwordx4 v[0:3], v[8:9], off offset:16
	global_load_dwordx4 v[4:7], v[8:9], off
	s_mov_b32 s37, s89
	v_lshl_add_u64 v[12:13], v[8:9], 0, s[54:55]
	v_mov_b32_e32 v59, 0
	v_lshl_add_u32 v90, s88, 6, v44
	s_add_i32 s61, s18, 0xffffff01
	s_mov_b32 s68, s88
	v_mov_b32_e32 v16, v59
	v_mov_b32_e32 v17, v59
	v_mov_b32_e32 v18, v59
	v_mov_b32_e32 v19, v59
	v_mov_b32_e32 v20, v59
	v_mov_b32_e32 v21, v59
	v_mov_b32_e32 v22, v59
	v_mov_b32_e32 v23, v59
	v_mov_b32_e32 v24, v59
	v_mov_b32_e32 v25, v59
	v_mov_b32_e32 v26, v59
	v_mov_b32_e32 v27, v59
	v_mov_b32_e32 v28, v59
	v_mov_b32_e32 v29, v59
	v_mov_b32_e32 v30, v59
	v_mov_b32_e32 v31, v59
	s_waitcnt vmcnt(0)
	ds_write_b128 v43, v[4:7]
	ds_write_b128 v43, v[0:3] offset:16
	v_or_b32_e32 v0, s48, v42
	v_mad_u64_u32 v[0:1], s[16:17], v0, s71, v[40:41]
	v_mad_u32_u24 v1, s49, v237, v1
	v_lshl_add_u64 v[0:1], v[0:1], 0, s[14:15]
	v_lshl_add_u64 v[0:1], v[0:1], 0, s[36:37]
	v_lshl_add_u64 v[2:3], v[0:1], 0, s[46:47]
	v_add_co_u32_e32 v0, vcc, s67, v0
	s_lshl_b32 s14, s18, 6
	s_nop 0
	v_addc_co_u32_e32 v1, vcc, 0, v1, vcc
	v_add_co_u32_e32 v8, vcc, s66, v8
	global_load_dwordx4 v[4:7], v[0:1], off
	s_nop 0
	global_load_dwordx4 v[0:3], v[2:3], off offset:16
	v_addc_co_u32_e32 v9, vcc, 0, v9, vcc
	global_load_dwordx4 v[8:11], v[8:9], off
	s_nop 0
	global_load_dwordx4 v[12:15], v[12:13], off offset:16
	v_subrev_u32_e32 v91, s14, v81
	v_sub_u32_e64 v212, s68, 1 clamp
	v_lshlrev_b64 v[144:145], 6, v[212:213]
	v_lshl_add_u64 v[146:147], v[144:145], 0, v[44:45]
	v_mad_u64_u32 v[148:149], s[18:19], v146, s71, v[40:41]
	v_mad_i32_i24 v149, v147, s71, v149
	s_lshl_b32 s16, s59, 1
	s_mov_b32 s17, s89
	v_lshl_add_u64 v[146:147], v[148:149], 0, s[16:17]
	v_lshl_add_u64 v[146:147], v[146:147], 0, v[56:57]
	v_lshl_add_u64 v[148:149], v[146:147], 0, s[54:55]
	v_add_co_u32_e32 v146, vcc, s66, v146
	v_or_b32_e32 v144, v144, v42
	s_nop 0
	v_addc_co_u32_e32 v147, vcc, 0, v147, vcc
	global_load_dwordx4 v[152:155], v[146:147], off
	global_load_dwordx4 v[156:159], v[148:149], off offset:16
	v_mad_u64_u32 v[146:147], s[18:19], v144, s71, v[40:41]
	v_mad_u32_u24 v147, v145, s71, v147
	v_lshl_add_u64 v[144:145], v[146:147], 0, s[16:17]
	v_lshl_add_u64 v[144:145], v[144:145], 0, s[36:37]
	v_lshl_add_u64 v[146:147], v[144:145], 0, s[46:47]
	v_add_co_u32_e32 v144, vcc, s67, v144
	s_nop 0
	v_addc_co_u32_e32 v145, vcc, 0, v145, vcc
	global_load_dwordx4 v[148:151], v[144:145], off
	s_nop 0
	global_load_dwordx4 v[144:147], v[146:147], off offset:16
	s_branch .LBB0_311

; __device__ __forceinline__ uint4 ldg16(const void* p) { const u32x4 v = *(const __attribute__((address_space(1))) u32x4*)(p); return make_uint4(v.x, v.y, v.z, v.w); }
; __device__ __forceinline__ void attn_phase(const Params& p, char* shmc, int tid, int wv) {
;     ...
;       {
;         *(uint4*)&Ks[krow * 136 + kc0] = ka;
;         *(uint4*)&Ks[krow * 136 + kc0 + 8] = kb4;
;         const unsigned vw[8] = {va.x, va.y, va.z, va.w, vb.x, vb.y, vb.z, vb.w};
; #pragma unroll
;         for (int i = 0; i < 8; ++i) { Vt[(vd0 + 2 * i) * 72 + vkey] = (u16)(vw[i] & 0xffffu); Vt[(vd0 + 2 * i + 1) * 72 + vkey] = (u16)(vw[i] >> 16); }
;       }
;       __syncthreads();
;       {
;         const int kn = kb > 0 ? kb - 1 : 0;
;         const u16* src = QKV + ((long)kn * 64 + krow) * 6144 + 2048 + h * 128 + kc0;
;         ka = ldg16(src); kb4 = ldg16(src + 8);
;         const u16* vs = QKV + ((long)kn * 64 + vkey) * 6144 + 4096 + h * 128 + vd0;
;         va = ldg16(vs); vb = ldg16(vs + 8);
;       }
;       {
;         const int ntb = (wv >> 2) * 2;
;         f32x4 z[2] = {{0.f, 0.f, 0.f, 0.f}, {0.f, 0.f, 0.f, 0.f}};
; #pragma unroll
;         for (int kk = 0; kk < 4; ++kk) {
;           const bf16x8 a = *(const bf16x8*)&Qs[(16 * mt + r) * 136 + kk * 32 + quad * 8];
; #pragma unroll
;           for (int i = 0; i < 2; ++i) {
;             const bf16x8 b = *(const bf16x8*)&Ks[(16 * (ntb + i) + r) * 136 + kk * 32 + quad * 8];
;             z[i] = __builtin_amdgcn_mfma_f32_16x16x32_bf16(a, b, z[i], 0, 0, 0);
;           }
;         }
; #pragma unroll
;         for (int i = 0; i < 2; ++i)
; #pragma unroll
;           for (int j = 0; j < 4; ++j) Zs[(16 * mt + 4 * quad + j) * 68 + 16 * (ntb + i) + r] = z[i][j] * 0.08838834764831845f;
;       }
;       __syncthreads();
;       {
;         const int row = tid >> 3, part = tid & 7;
;         const float4 za = *(const float4*)&Zs[row * 68 + part * 8], zb = *(const float4*)&Zs[row * 68 + part * 8 + 4];
;         const float z[8] = {za.x, za.y, za.z, za.w, zb.x, zb.y, zb.z, zb.w};
;         const int qpos = qb * 64 + row, kpos0 = kb * 64 + part * 8;
;         float sp[8];
;         float ptot = 0.f;
; #pragma unroll
;         for (int i = 0; i < 8; ++i) {
;           const bool valid = (kpos0 + i) < qpos;
;           sp[i] = valid ? (fmaxf(z[i], 0.f) + __logf(1.f + __expf(-fabsf(z[i])))) : 0.f;
.LBB0_310:
	s_add_i32 s68, s68, -1
	s_cmp_lg_u32 s61, 0
	v_cmp_ne_u32_e32 vcc, 0, v32
	s_cselect_b64 s[14:15], -1, 0
	s_and_b64 s[14:15], vcc, s[14:15]
	s_add_i32 s61, s61, 1
	v_subrev_u32_e32 v91, 64, v91
	s_and_b64 vcc, exec, s[14:15]
	s_cbranch_vccz .LBB0_307
	s_branch .Lat_bodyB
.LBB0_311:
	v_sub_u32_e64 v212, s68, 2 clamp
	s_waitcnt vmcnt(5)
	ds_write_b128 v43, v[8:11] offset:17408
	s_waitcnt vmcnt(4)
	ds_write_b128 v43, v[12:15] offset:17424
	ds_write_b16 v77, v4 offset:34816
	ds_write_b16_d16_hi v77, v4 offset:34960
	ds_write_b16 v77, v5 offset:35104
	ds_write_b16_d16_hi v77, v5 offset:35248
	ds_write_b16 v77, v6 offset:35392
	ds_write_b16_d16_hi v77, v6 offset:35536
	ds_write_b16 v77, v7 offset:35680
	ds_write_b16_d16_hi v77, v7 offset:35824
	ds_write_b16 v77, v0 offset:35968
	ds_write_b16_d16_hi v77, v0 offset:36112
	ds_write_b16 v77, v1 offset:36256
	ds_write_b16_d16_hi v77, v1 offset:36400
	ds_write_b16 v77, v2 offset:36544
	ds_write_b16_d16_hi v77, v2 offset:36688
	ds_write_b16 v77, v3 offset:36832
	ds_write_b16_d16_hi v77, v3 offset:36976
	v_lshlrev_b64 v[0:1], 6, v[212:213]
	v_lshl_add_u64 v[2:3], v[0:1], 0, v[44:45]
	v_mad_u64_u32 v[4:5], s[14:15], v2, s71, v[40:41]
	v_mad_i32_i24 v5, v3, s71, v5
	s_lshl_b32 s88, s59, 1
	v_lshl_add_u64 v[2:3], v[4:5], 0, s[88:89]
	v_lshl_add_u64 v[2:3], v[2:3], 0, v[56:57]
	v_lshl_add_u64 v[4:5], v[2:3], 0, s[54:55]
	v_add_co_u32_e32 v2, vcc, s66, v2
	v_or_b32_e32 v0, v0, v42
	s_nop 0
	v_addc_co_u32_e32 v3, vcc, 0, v3, vcc
	s_waitcnt lgkmcnt(0)
	s_barrier
	global_load_dwordx4 v[8:11], v[2:3], off
	global_load_dwordx4 v[12:15], v[4:5], off offset:16
	v_mad_u64_u32 v[2:3], s[14:15], v0, s71, v[40:41]
	v_mad_u32_u24 v3, v1, s71, v3
	v_lshl_add_u64 v[0:1], v[2:3], 0, s[88:89]
	v_lshl_add_u64 v[0:1], v[0:1], 0, s[36:37]
	v_lshl_add_u64 v[2:3], v[0:1], 0, s[46:47]
	v_add_co_u32_e32 v0, vcc, s67, v0
	v_add_u32_e32 v58, 0xd000, v84
	s_nop 0
	v_addc_co_u32_e32 v1, vcc, 0, v1, vcc
	global_load_dwordx4 v[4:7], v[0:1], off
	s_nop 0
	global_load_dwordx4 v[0:3], v[2:3], off offset:16
	ds_read_b128 v[96:99], v47
	ds_read_b128 v[112:115], v82 offset:17408
	ds_read_b128 v[128:131], v83 offset:17408
	ds_read_b128 v[100:103], v47 offset:64
	ds_read_b128 v[116:119], v82 offset:17472
	ds_read_b128 v[132:135], v83 offset:17472
	ds_read_b128 v[104:107], v47 offset:128
	ds_read_b128 v[120:123], v82 offset:17536
	ds_read_b128 v[136:139], v83 offset:17536
	ds_read_b128 v[108:111], v47 offset:192
	ds_read_b128 v[124:127], v82 offset:17600
	ds_read_b128 v[140:143], v83 offset:17600
	s_waitcnt lgkmcnt(10)
	v_mfma_f32_16x16x32_bf16 v[36:39], v[96:99], v[112:115], 0
	s_waitcnt lgkmcnt(9)
	v_mfma_f32_16x16x32_bf16 v[32:35], v[96:99], v[128:131], 0
	s_waitcnt lgkmcnt(7)
	v_mfma_f32_16x16x32_bf16 v[36:39], v[100:103], v[116:119], v[36:39]
	s_waitcnt lgkmcnt(6)
	v_mfma_f32_16x16x32_bf16 v[32:35], v[100:103], v[132:135], v[32:35]
	s_waitcnt lgkmcnt(4)
	v_mfma_f32_16x16x32_bf16 v[36:39], v[104:107], v[120:123], v[36:39]
	s_waitcnt lgkmcnt(3)
	v_mfma_f32_16x16x32_bf16 v[32:35], v[104:107], v[136:139], v[32:35]
	s_waitcnt lgkmcnt(1)
	v_mfma_f32_16x16x32_bf16 v[36:39], v[108:111], v[124:127], v[36:39]
	s_waitcnt lgkmcnt(0)
	v_mfma_f32_16x16x32_bf16 v[32:35], v[108:111], v[140:143], v[32:35]
	s_nop 7
	v_mul_f32_e32 v36, 0x3db504f3, v36
	v_mul_f32_e32 v37, 0x3db504f3, v37
	ds_write2_b32 v58, v36, v37 offset1:68
	v_mul_f32_e32 v36, 0x3db504f3, v38
	v_mul_f32_e32 v37, 0x3db504f3, v39
	ds_write2_b32 v58, v36, v37 offset0:136 offset1:204
	v_mul_f32_e32 v32, 0x3db504f3, v32
	v_mul_f32_e32 v33, 0x3db504f3, v33
	v_add_u32_e32 v36, 0xd000, v85
	ds_write2_b32 v36, v32, v33 offset1:68
	v_mul_f32_e32 v32, 0x3db504f3, v34
	v_mul_f32_e32 v33, 0x3db504f3, v35
	ds_write2_b32 v36, v32, v33 offset0:136 offset1:204
	s_waitcnt lgkmcnt(0)
	s_barrier
	ds_read_b128 v[32:35], v51 offset:53248
	ds_read_b128 v[36:39], v51 offset:53264
	v_add_u32_e32 v58, -7, v91
	v_cmp_lt_i32_e32 vcc, v58, v90
	v_add_u32_e32 v58, -6, v91
	v_cmp_lt_i32_e64 s[14:15], v58, v90
	v_add_u32_e32 v58, -5, v91
	v_cmp_lt_i32_e64 s[16:17], v58, v90
	v_add_u32_e32 v58, -4, v91
	v_cmp_lt_i32_e64 s[18:19], v58, v90
	v_add_u32_e32 v58, -3, v91
	v_cmp_lt_i32_e64 s[20:21], v58, v90
	v_add_u32_e32 v58, -2, v91
	v_cmp_lt_i32_e64 s[22:23], v58, v90
	v_add_u32_e32 v58, -1, v91
	v_cmp_lt_i32_e64 s[24:25], v58, v90
	v_cmp_lt_i32_e64 s[26:27], v91, v90
	s_waitcnt lgkmcnt(0)
; __device__ __forceinline__ unsigned pack2(float a, float b) { const f32v2_ v = {a, b}; const bf16v2_ r = __builtin_convertvector(v, bf16v2_); return __builtin_bit_cast(unsigned, r); }
; __device__ __forceinline__ float shfl_idx(float v, int srclane) { return __int_as_float(__builtin_amdgcn_ds_bpermute(srclane << 2, __float_as_int(v))); }
; __device__ __forceinline__ void attn_phase(const Params& p, char* shmc, int tid, int wv) {
;     ...
;         const int row = tid >> 3, part = tid & 7;
;         const float4 za = *(const float4*)&Zs[row * 68 + part * 8], zb = *(const float4*)&Zs[row * 68 + part * 8 + 4];
;         const float z[8] = {za.x, za.y, za.z, za.w, zb.x, zb.y, zb.z, zb.w};
;         const int qpos = qb * 64 + row, kpos0 = kb * 64 + part * 8;
;         float sp[8];
;         float ptot = 0.f;
; #pragma unroll
;         for (int i = 0; i < 8; ++i) {
;           const bool valid = (kpos0 + i) < qpos;
;           sp[i] = valid ? (fmaxf(z[i], 0.f) + __logf(1.f + __expf(-fabsf(z[i])))) : 0.f;
;           ptot += sp[i];
;         }
;         float tot = ptot;
; #pragma unroll
;         for (int o = 1; o < 8; o <<= 1) { const float v = shfl_idx(tot, lane + o); if (part + o < 8) tot += v; }
;         float running = carry - (tot - ptot);
;         float a[8];
; #pragma unroll
;         for (int i = 7; i >= 0; --i) {
;           const bool valid = (kpos0 + i) < qpos;
;           a[i] = valid ? __expf(z[i] - sp[i] + running) : 0.f;
;           running -= sp[i];
;         }
;         const float all = shfl_idx(tot, lane & ~7);
;         carry -= all;
;         *(uint4*)&Ps[row * 72 + part * 8] = make_uint4(pack2(a[0], a[1]), pack2(a[2], a[3]), pack2(a[4], a[5]), pack2(a[6], a[7]));
	v_mul_f32_e64 v96, |v32|, s74
	v_mul_f32_e64 v97, |v33|, s74
	v_mul_f32_e64 v98, |v34|, s74
	v_mul_f32_e64 v99, |v35|, s74
	v_mul_f32_e64 v100, |v36|, s74
	v_mul_f32_e64 v101, |v37|, s74
	v_mul_f32_e64 v102, |v38|, s74
	v_mul_f32_e64 v103, |v39|, s74
	v_exp_f32_e32 v96, v96
	v_exp_f32_e32 v97, v97
	v_exp_f32_e32 v98, v98
	v_exp_f32_e32 v99, v99
	v_exp_f32_e32 v100, v100
	v_exp_f32_e32 v101, v101
	v_exp_f32_e32 v102, v102
	v_exp_f32_e32 v103, v103
	v_max_f32_e32 v60, v32, v32
	v_max_f32_e32 v62, v33, v33
	v_max_f32_e32 v64, v34, v34
	v_max_f32_e32 v66, v35, v35
	v_max_f32_e32 v68, v36, v36
	v_max_f32_e32 v70, v37, v37
	v_max_f32_e32 v72, v38, v38
	v_max_f32_e32 v74, v39, v39
	v_add_f32_e32 v96, 1.0, v96
	v_add_f32_e32 v97, 1.0, v97
	v_add_f32_e32 v98, 1.0, v98
	v_add_f32_e32 v99, 1.0, v99
	v_add_f32_e32 v100, 1.0, v100
	v_add_f32_e32 v101, 1.0, v101
	v_add_f32_e32 v102, 1.0, v102
	v_add_f32_e32 v103, 1.0, v103
	v_log_f32_e32 v96, v96
	v_log_f32_e32 v97, v97
	v_log_f32_e32 v98, v98
	v_log_f32_e32 v99, v99
	v_log_f32_e32 v100, v100
	v_log_f32_e32 v101, v101
	v_log_f32_e32 v102, v102
	v_log_f32_e32 v103, v103
	v_max_f32_e32 v60, 0, v60
	v_max_f32_e32 v62, 0, v62
	v_max_f32_e32 v64, 0, v64
	v_max_f32_e32 v66, 0, v66
	v_max_f32_e32 v68, 0, v68
	v_max_f32_e32 v70, 0, v70
	v_max_f32_e32 v72, 0, v72
	v_max_f32_e32 v74, 0, v74
	v_mul_f32_e32 v104, 0x3f317217, v96
	v_mul_f32_e32 v105, 0x3f317217, v97
	v_mul_f32_e32 v106, 0x3f317217, v98
	v_mul_f32_e32 v107, 0x3f317217, v99
	v_mul_f32_e32 v108, 0x3f317217, v100
	v_mul_f32_e32 v109, 0x3f317217, v101
	v_mul_f32_e32 v110, 0x3f317217, v102
	v_mul_f32_e32 v111, 0x3f317217, v103
	v_fma_f32 v104, v96, s75, -v104
	v_fma_f32 v105, v97, s75, -v105
	v_fma_f32 v106, v98, s75, -v106
	v_fma_f32 v107, v99, s75, -v107
	v_fma_f32 v108, v100, s75, -v108
	v_fma_f32 v109, v101, s75, -v109
	v_fma_f32 v110, v102, s75, -v110
	v_fma_f32 v111, v103, s75, -v111
	v_fmac_f32_e32 v104, 0x3377d1cf, v96
	v_fmac_f32_e32 v105, 0x3377d1cf, v97
	v_fmac_f32_e32 v106, 0x3377d1cf, v98
	v_fmac_f32_e32 v107, 0x3377d1cf, v99
	v_fmac_f32_e32 v108, 0x3377d1cf, v100
	v_fmac_f32_e32 v109, 0x3377d1cf, v101
	v_fmac_f32_e32 v110, 0x3377d1cf, v102
	v_fmac_f32_e32 v111, 0x3377d1cf, v103
	v_fmac_f32_e32 v104, 0x3f317217, v96
	v_fmac_f32_e32 v105, 0x3f317217, v97
	v_fmac_f32_e32 v106, 0x3f317217, v98
	v_fmac_f32_e32 v107, 0x3f317217, v99
	v_fmac_f32_e32 v108, 0x3f317217, v100
	v_fmac_f32_e32 v109, 0x3f317217, v101
	v_fmac_f32_e32 v110, 0x3f317217, v102
	v_fmac_f32_e32 v111, 0x3f317217, v103
	v_add_f32_e32 v60, v60, v104
	v_add_f32_e32 v62, v62, v105
	v_add_f32_e32 v64, v64, v106
	v_add_f32_e32 v66, v66, v107
	v_add_f32_e32 v68, v68, v108
	v_add_f32_e32 v70, v70, v109
	v_add_f32_e32 v72, v72, v110
	v_add_f32_e32 v74, v74, v111
	v_cndmask_b32_e32 v60, 0, v60, vcc
	v_cndmask_b32_e64 v62, 0, v62, s[14:15]
	v_cndmask_b32_e64 v64, 0, v64, s[16:17]
	v_cndmask_b32_e64 v66, 0, v66, s[18:19]
	v_cndmask_b32_e64 v68, 0, v68, s[20:21]
	v_cndmask_b32_e64 v70, 0, v70, s[22:23]
	v_cndmask_b32_e64 v72, 0, v72, s[24:25]
	v_cndmask_b32_e64 v74, 0, v74, s[26:27]
	v_add_f32_e32 v58, 0, v60
	v_add_f32_e32 v58, v58, v62
	v_add_f32_e32 v58, v58, v64
	v_add_f32_e32 v58, v58, v66
	v_add_f32_e32 v58, v58, v68
	v_add_f32_e32 v58, v58, v70
	v_add_f32_e32 v58, v58, v72
	v_add_f32_e32 v58, v58, v74
	ds_bpermute_b32 v61, v78, v58
	v_mov_b32_e32 v73, v74
	v_mov_b32_e32 v71, v72
	v_mov_b32_e32 v69, v70
	v_mov_b32_e32 v67, v68
	s_waitcnt lgkmcnt(0)
	v_add_f32_e32 v61, v58, v61
	v_cndmask_b32_e64 v61, v61, v58, s[8:9]
	ds_bpermute_b32 v63, v79, v61
	v_mov_b32_e32 v65, v66
	s_bitcmp1_b32 exec_hi, 0
	s_waitcnt lgkmcnt(0)
	v_add_f32_e32 v63, v61, v63
	v_cndmask_b32_e64 v61, v61, v63, s[10:11]
	ds_bpermute_b32 v63, v80, v61
	s_waitcnt lgkmcnt(0)
	v_add_f32_e32 v63, v61, v63
	v_cndmask_b32_e64 v94, v61, v63, s[12:13]
	v_sub_f32_e32 v75, v94, v58
	v_mov_b32_e32 v58, v39
	v_pk_add_f32 v[92:93], v[58:59], v[74:75] neg_lo:[0,1] neg_hi:[0,1]
	v_mov_b32_e32 v63, v64
	v_add_f32_e32 v39, v92, v93
	v_mul_f32_e32 v39, 0x3fb8aa3b, v39
	v_exp_f32_e32 v39, v39
	v_mov_b32_e32 v61, v62
	v_cndmask_b32_e64 v58, 0, v39, s[26:27]
	v_mov_b32_e32 v39, v93
	v_pk_add_f32 v[38:39], v[38:39], v[72:73] neg_lo:[0,1] neg_hi:[0,1]
	s_nop 0
	v_add_f32_e32 v38, v38, v39
	v_mul_f32_e32 v38, 0x3fb8aa3b, v38
	v_exp_f32_e32 v38, v38
	s_nop 0
	v_cndmask_b32_e64 v73, 0, v38, s[24:25]
	v_mov_b32_e32 v38, v37
	v_pk_add_f32 v[38:39], v[38:39], v[70:71] neg_lo:[0,1] neg_hi:[0,1]
	s_nop 0
	v_add_f32_e32 v37, v38, v39
	v_mul_f32_e32 v37, 0x3fb8aa3b, v37
	v_exp_f32_e32 v37, v37
	s_nop 0
	v_cndmask_b32_e64 v38, 0, v37, s[22:23]
	v_mov_b32_e32 v37, v39
	v_pk_add_f32 v[36:37], v[36:37], v[68:69] neg_lo:[0,1] neg_hi:[0,1]
	s_nop 0
	v_add_f32_e32 v36, v36, v37
	v_mul_f32_e32 v36, 0x3fb8aa3b, v36
	v_exp_f32_e32 v36, v36
	s_nop 0
	v_cndmask_b32_e64 v39, 0, v36, s[20:21]
	v_mov_b32_e32 v36, v35
	v_pk_add_f32 v[36:37], v[36:37], v[66:67] neg_lo:[0,1] neg_hi:[0,1]
	s_nop 0
	v_add_f32_e32 v35, v36, v37
	v_mul_f32_e32 v35, 0x3fb8aa3b, v35
	v_exp_f32_e32 v35, v35
	s_nop 0
	v_cndmask_b32_e64 v36, 0, v35, s[18:19]
	v_mov_b32_e32 v35, v37
	v_pk_add_f32 v[34:35], v[34:35], v[64:65] neg_lo:[0,1] neg_hi:[0,1]
	s_nop 0
	v_add_f32_e32 v34, v34, v35
	v_mul_f32_e32 v34, 0x3fb8aa3b, v34
	v_exp_f32_e32 v34, v34
	s_nop 0
	v_cndmask_b32_e64 v37, 0, v34, s[16:17]
	v_mov_b32_e32 v34, v33
	v_pk_add_f32 v[34:35], v[34:35], v[62:63] neg_lo:[0,1] neg_hi:[0,1]
	s_nop 0
	v_add_f32_e32 v33, v34, v35
	v_mul_f32_e32 v33, 0x3fb8aa3b, v33
	v_exp_f32_e32 v33, v33
	s_nop 0
	v_cndmask_b32_e64 v34, 0, v33, s[14:15]
	v_mov_b32_e32 v33, v35
	v_pk_add_f32 v[32:33], v[32:33], v[60:61] neg_lo:[0,1] neg_hi:[0,1]
	v_cvt_pk_bf16_f32 v35, v73, v58
	v_add_f32_e32 v32, v32, v33
	v_mul_f32_e32 v32, 0x3fb8aa3b, v32
	v_exp_f32_e32 v32, v32
	v_cvt_pk_bf16_f32 v33, v37, v36
	ds_bpermute_b32 v60, v53, v94
	s_mov_b32 s14, 0xc2f00000
	v_cndmask_b32_e32 v32, 0, v32, vcc
	v_cvt_pk_bf16_f32 v32, v32, v34
	v_cvt_pk_bf16_f32 v34, v39, v38
	ds_write_b128 v55, v[32:35]
	s_waitcnt lgkmcnt(0)
	s_barrier
; __device__ __forceinline__ void attn_phase(const Params& p, char* shmc, int tid, int wv) {
;     ...
;       {
;         const int ntb = (wv >> 2) * 4;
; #pragma unroll
;         for (int kk = 0; kk < 2; ++kk) {
;           const bf16x8 a = *(const bf16x8*)&Ps[(16 * mt + r) * 72 + kk * 32 + quad * 8];
; #pragma unroll
;           for (int i = 0; i < 4; ++i) {
;             const bf16x8 b = *(const bf16x8*)&Vt[(16 * (ntb + i) + r) * 72 + kk * 32 + quad * 8];
;             oacc[i] = __builtin_amdgcn_mfma_f32_16x16x32_bf16(a, b, oacc[i], 0, 0, 0);
;           }
;         }
;       }
;       const int more = __syncthreads_or(carry > -120.f);
;       if (!more) break;
	ds_read_b128 v[96:99], v76
	ds_read_b128 v[104:107], v86 offset:34816
	ds_read_b128 v[108:111], v87 offset:34816
	ds_read_b128 v[112:115], v88 offset:34816
	ds_read_b128 v[116:119], v89 offset:34816
	ds_read_b128 v[100:103], v76 offset:64
	ds_read_b128 v[120:123], v86 offset:34880
	ds_read_b128 v[124:127], v87 offset:34880
	ds_read_b128 v[128:131], v88 offset:34880
	ds_read_b128 v[132:135], v89 offset:34880
	v_sub_f32_e32 v59, v59, v60
	v_cmp_lt_f32_e32 vcc, s14, v59
	s_waitcnt lgkmcnt(8)
	v_mfma_f32_16x16x32_bf16 v[16:19], v[96:99], v[104:107], v[16:19]
	s_waitcnt lgkmcnt(7)
	v_mfma_f32_16x16x32_bf16 v[20:23], v[96:99], v[108:111], v[20:23]
	s_waitcnt lgkmcnt(6)
	v_mfma_f32_16x16x32_bf16 v[24:27], v[96:99], v[112:115], v[24:27]
	s_waitcnt lgkmcnt(5)
	v_mfma_f32_16x16x32_bf16 v[28:31], v[96:99], v[116:119], v[28:31]
	s_waitcnt lgkmcnt(3)
	v_mfma_f32_16x16x32_bf16 v[16:19], v[100:103], v[120:123], v[16:19]
	s_waitcnt lgkmcnt(2)
	v_mfma_f32_16x16x32_bf16 v[20:23], v[100:103], v[124:127], v[20:23]
	s_waitcnt lgkmcnt(1)
	v_mfma_f32_16x16x32_bf16 v[24:27], v[100:103], v[128:131], v[24:27]
	s_waitcnt lgkmcnt(0)
	v_mfma_f32_16x16x32_bf16 v[28:31], v[100:103], v[132:135], v[28:31]
	s_cmp_lg_u64 vcc, 0
	s_cselect_b32 s16, 1, 0
	v_mov_b32_e32 v32, s16
	s_andn2_b64 vcc, exec, s[94:95]
	s_cbranch_vccnz .LBB0_310
	s_and_saveexec_b64 s[14:15], s[4:5]
	v_mov_b32_e32 v32, s16
	ds_write_b32 v213, v32
	s_or_b64 exec, exec, s[14:15]
	s_waitcnt lgkmcnt(0)
	s_barrier
	s_and_saveexec_b64 s[14:15], s[98:99]
	s_cbranch_execz .LBB0_309
	v_mbcnt_lo_u32_b32 v32, exec_lo, 0
	v_mbcnt_hi_u32_b32 v32, exec_hi, v32
	v_cmp_eq_u32_e32 vcc, 0, v32
	s_and_b64 exec, exec, vcc
	s_cbranch_execz .LBB0_309
	v_mov_b32_e32 v32, s16
	ds_or_b32 v213, v32
	s_branch .LBB0_309

; __device__ __forceinline__ uint4 ldg16(const void* p) { const u32x4 v = *(const __attribute__((address_space(1))) u32x4*)(p); return make_uint4(v.x, v.y, v.z, v.w); }
; __device__ __forceinline__ void attn_phase(const Params& p, char* shmc, int tid, int wv) {
;     ...
;       {
;         *(uint4*)&Ks[krow * 136 + kc0] = ka;
;         *(uint4*)&Ks[krow * 136 + kc0 + 8] = kb4;
;         const unsigned vw[8] = {va.x, va.y, va.z, va.w, vb.x, vb.y, vb.z, vb.w};
; #pragma unroll
;         for (int i = 0; i < 8; ++i) { Vt[(vd0 + 2 * i) * 72 + vkey] = (u16)(vw[i] & 0xffffu); Vt[(vd0 + 2 * i + 1) * 72 + vkey] = (u16)(vw[i] >> 16); }
;       }
;       __syncthreads();
;       {
;         const int kn = kb > 0 ? kb - 1 : 0;
;         const u16* src = QKV + ((long)kn * 64 + krow) * 6144 + 2048 + h * 128 + kc0;
;         ka = ldg16(src); kb4 = ldg16(src + 8);
;         const u16* vs = QKV + ((long)kn * 64 + vkey) * 6144 + 4096 + h * 128 + vd0;
;         va = ldg16(vs); vb = ldg16(vs + 8);
;       }
;       {
;         const int ntb = (wv >> 2) * 2;
;         f32x4 z[2] = {{0.f, 0.f, 0.f, 0.f}, {0.f, 0.f, 0.f, 0.f}};
; #pragma unroll
;         for (int kk = 0; kk < 4; ++kk) {
;           const bf16x8 a = *(const bf16x8*)&Qs[(16 * mt + r) * 136 + kk * 32 + quad * 8];
; #pragma unroll
;           for (int i = 0; i < 2; ++i) {
;             const bf16x8 b = *(const bf16x8*)&Ks[(16 * (ntb + i) + r) * 136 + kk * 32 + quad * 8];
;             z[i] = __builtin_amdgcn_mfma_f32_16x16x32_bf16(a, b, z[i], 0, 0, 0);
;           }
;         }
; #pragma unroll
;         for (int i = 0; i < 2; ++i)
; #pragma unroll
;           for (int j = 0; j < 4; ++j) Zs[(16 * mt + 4 * quad + j) * 68 + 16 * (ntb + i) + r] = z[i][j] * 0.08838834764831845f;
;       }
;       __syncthreads();
;       {
;         const int row = tid >> 3, part = tid & 7;
;         const float4 za = *(const float4*)&Zs[row * 68 + part * 8], zb = *(const float4*)&Zs[row * 68 + part * 8 + 4];
;         const float z[8] = {za.x, za.y, za.z, za.w, zb.x, zb.y, zb.z, zb.w};
;         const int qpos = qb * 64 + row, kpos0 = kb * 64 + part * 8;
;         float sp[8];
;         float ptot = 0.f;
; #pragma unroll
;         for (int i = 0; i < 8; ++i) {
;           const bool valid = (kpos0 + i) < qpos;
;           sp[i] = valid ? (fmaxf(z[i], 0.f) + __logf(1.f + __expf(-fabsf(z[i])))) : 0.f;
.Lat_bodyB:
	v_sub_u32_e64 v212, s68, 2 clamp
	s_waitcnt vmcnt(5)
	ds_write_b128 v43, v[152:155] offset:17408
	s_waitcnt vmcnt(4)
	ds_write_b128 v43, v[156:159] offset:17424
	ds_write_b16 v77, v148 offset:34816
	ds_write_b16_d16_hi v77, v148 offset:34960
	ds_write_b16 v77, v149 offset:35104
	ds_write_b16_d16_hi v77, v149 offset:35248
	ds_write_b16 v77, v150 offset:35392
	ds_write_b16_d16_hi v77, v150 offset:35536
	ds_write_b16 v77, v151 offset:35680
	ds_write_b16_d16_hi v77, v151 offset:35824
	ds_write_b16 v77, v144 offset:35968
	ds_write_b16_d16_hi v77, v144 offset:36112
	ds_write_b16 v77, v145 offset:36256
	ds_write_b16_d16_hi v77, v145 offset:36400
	ds_write_b16 v77, v146 offset:36544
	ds_write_b16_d16_hi v77, v146 offset:36688
	ds_write_b16 v77, v147 offset:36832
	ds_write_b16_d16_hi v77, v147 offset:36976
	v_lshlrev_b64 v[144:145], 6, v[212:213]
	v_lshl_add_u64 v[146:147], v[144:145], 0, v[44:45]
	v_mad_u64_u32 v[148:149], s[14:15], v146, s71, v[40:41]
	v_mad_i32_i24 v149, v147, s71, v149
	s_lshl_b32 s88, s59, 1
	v_lshl_add_u64 v[146:147], v[148:149], 0, s[88:89]
	v_lshl_add_u64 v[146:147], v[146:147], 0, v[56:57]
	v_lshl_add_u64 v[148:149], v[146:147], 0, s[54:55]
	v_add_co_u32_e32 v146, vcc, s66, v146
	v_or_b32_e32 v144, v144, v42
	s_nop 0
	v_addc_co_u32_e32 v147, vcc, 0, v147, vcc
	s_waitcnt lgkmcnt(0)
	s_barrier
	global_load_dwordx4 v[152:155], v[146:147], off
	global_load_dwordx4 v[156:159], v[148:149], off offset:16
	v_mad_u64_u32 v[146:147], s[14:15], v144, s71, v[40:41]
	v_mad_u32_u24 v147, v145, s71, v147
	v_lshl_add_u64 v[144:145], v[146:147], 0, s[88:89]
	v_lshl_add_u64 v[144:145], v[144:145], 0, s[36:37]
	v_lshl_add_u64 v[146:147], v[144:145], 0, s[46:47]
	v_add_co_u32_e32 v144, vcc, s67, v144
	v_add_u32_e32 v58, 0xd000, v84
	s_nop 0
	v_addc_co_u32_e32 v145, vcc, 0, v145, vcc
	global_load_dwordx4 v[148:151], v[144:145], off
	s_nop 0
	global_load_dwordx4 v[144:147], v[146:147], off offset:16
	ds_read_b128 v[96:99], v47
	ds_read_b128 v[112:115], v82 offset:17408
	ds_read_b128 v[128:131], v83 offset:17408
	ds_read_b128 v[100:103], v47 offset:64
	ds_read_b128 v[116:119], v82 offset:17472
	ds_read_b128 v[132:135], v83 offset:17472
	ds_read_b128 v[104:107], v47 offset:128
	ds_read_b128 v[120:123], v82 offset:17536
	ds_read_b128 v[136:139], v83 offset:17536
	ds_read_b128 v[108:111], v47 offset:192
	ds_read_b128 v[124:127], v82 offset:17600
	ds_read_b128 v[140:143], v83 offset:17600
	s_waitcnt lgkmcnt(10)
	v_mfma_f32_16x16x32_bf16 v[36:39], v[96:99], v[112:115], 0
	s_waitcnt lgkmcnt(9)
	v_mfma_f32_16x16x32_bf16 v[32:35], v[96:99], v[128:131], 0
	s_waitcnt lgkmcnt(7)
	v_mfma_f32_16x16x32_bf16 v[36:39], v[100:103], v[116:119], v[36:39]
	s_waitcnt lgkmcnt(6)
	v_mfma_f32_16x16x32_bf16 v[32:35], v[100:103], v[132:135], v[32:35]
	s_waitcnt lgkmcnt(4)
	v_mfma_f32_16x16x32_bf16 v[36:39], v[104:107], v[120:123], v[36:39]
	s_waitcnt lgkmcnt(3)
	v_mfma_f32_16x16x32_bf16 v[32:35], v[104:107], v[136:139], v[32:35]
	s_waitcnt lgkmcnt(1)
	v_mfma_f32_16x16x32_bf16 v[36:39], v[108:111], v[124:127], v[36:39]
	s_waitcnt lgkmcnt(0)
	v_mfma_f32_16x16x32_bf16 v[32:35], v[108:111], v[140:143], v[32:35]
	s_nop 7
	v_mul_f32_e32 v36, 0x3db504f3, v36
	v_mul_f32_e32 v37, 0x3db504f3, v37
	ds_write2_b32 v58, v36, v37 offset1:68
	v_mul_f32_e32 v36, 0x3db504f3, v38
	v_mul_f32_e32 v37, 0x3db504f3, v39
	ds_write2_b32 v58, v36, v37 offset0:136 offset1:204
	v_mul_f32_e32 v32, 0x3db504f3, v32
	v_mul_f32_e32 v33, 0x3db504f3, v33
	v_add_u32_e32 v36, 0xd000, v85
	ds_write2_b32 v36, v32, v33 offset1:68
	v_mul_f32_e32 v32, 0x3db504f3, v34
	v_mul_f32_e32 v33, 0x3db504f3, v35
	ds_write2_b32 v36, v32, v33 offset0:136 offset1:204
	s_waitcnt lgkmcnt(0)
	s_barrier
	ds_read_b128 v[32:35], v51 offset:53248
	ds_read_b128 v[36:39], v51 offset:53264
	v_add_u32_e32 v58, -7, v91
	v_cmp_lt_i32_e32 vcc, v58, v90
	v_add_u32_e32 v58, -6, v91
	v_cmp_lt_i32_e64 s[14:15], v58, v90
	v_add_u32_e32 v58, -5, v91
	v_cmp_lt_i32_e64 s[16:17], v58, v90
	v_add_u32_e32 v58, -4, v91
	v_cmp_lt_i32_e64 s[18:19], v58, v90
	v_add_u32_e32 v58, -3, v91
	v_cmp_lt_i32_e64 s[20:21], v58, v90
	v_add_u32_e32 v58, -2, v91
	v_cmp_lt_i32_e64 s[22:23], v58, v90
	v_add_u32_e32 v58, -1, v91
	v_cmp_lt_i32_e64 s[24:25], v58, v90
	v_cmp_lt_i32_e64 s[26:27], v91, v90
	s_waitcnt lgkmcnt(0)
; __device__ __forceinline__ unsigned pack2(float a, float b) { const f32v2_ v = {a, b}; const bf16v2_ r = __builtin_convertvector(v, bf16v2_); return __builtin_bit_cast(unsigned, r); }
; __device__ __forceinline__ float shfl_idx(float v, int srclane) { return __int_as_float(__builtin_amdgcn_ds_bpermute(srclane << 2, __float_as_int(v))); }
; __device__ __forceinline__ void attn_phase(const Params& p, char* shmc, int tid, int wv) {
;     ...
;         const int row = tid >> 3, part = tid & 7;
;         const float4 za = *(const float4*)&Zs[row * 68 + part * 8], zb = *(const float4*)&Zs[row * 68 + part * 8 + 4];
;         const float z[8] = {za.x, za.y, za.z, za.w, zb.x, zb.y, zb.z, zb.w};
;         const int qpos = qb * 64 + row, kpos0 = kb * 64 + part * 8;
;         float sp[8];
;         float ptot = 0.f;
; #pragma unroll
;         for (int i = 0; i < 8; ++i) {
;           const bool valid = (kpos0 + i) < qpos;
;           sp[i] = valid ? (fmaxf(z[i], 0.f) + __logf(1.f + __expf(-fabsf(z[i])))) : 0.f;
;           ptot += sp[i];
;         }
;         float tot = ptot;
; #pragma unroll
;         for (int o = 1; o < 8; o <<= 1) { const float v = shfl_idx(tot, lane + o); if (part + o < 8) tot += v; }
;         float running = carry - (tot - ptot);
;         float a[8];
; #pragma unroll
;         for (int i = 7; i >= 0; --i) {
;           const bool valid = (kpos0 + i) < qpos;
;           a[i] = valid ? __expf(z[i] - sp[i] + running) : 0.f;
;           running -= sp[i];
;         }
;         const float all = shfl_idx(tot, lane & ~7);
;         carry -= all;
;         *(uint4*)&Ps[row * 72 + part * 8] = make_uint4(pack2(a[0], a[1]), pack2(a[2], a[3]), pack2(a[4], a[5]), pack2(a[6], a[7]));
	v_mul_f32_e64 v96, |v32|, s74
	v_mul_f32_e64 v97, |v33|, s74
	v_mul_f32_e64 v98, |v34|, s74
	v_mul_f32_e64 v99, |v35|, s74
	v_mul_f32_e64 v100, |v36|, s74
	v_mul_f32_e64 v101, |v37|, s74
	v_mul_f32_e64 v102, |v38|, s74
	v_mul_f32_e64 v103, |v39|, s74
	v_exp_f32_e32 v96, v96
	v_exp_f32_e32 v97, v97
	v_exp_f32_e32 v98, v98
	v_exp_f32_e32 v99, v99
	v_exp_f32_e32 v100, v100
	v_exp_f32_e32 v101, v101
	v_exp_f32_e32 v102, v102
	v_exp_f32_e32 v103, v103
	v_max_f32_e32 v60, v32, v32
	v_max_f32_e32 v62, v33, v33
	v_max_f32_e32 v64, v34, v34
	v_max_f32_e32 v66, v35, v35
	v_max_f32_e32 v68, v36, v36
	v_max_f32_e32 v70, v37, v37
	v_max_f32_e32 v72, v38, v38
	v_max_f32_e32 v74, v39, v39
	v_add_f32_e32 v96, 1.0, v96
	v_add_f32_e32 v97, 1.0, v97
	v_add_f32_e32 v98, 1.0, v98
	v_add_f32_e32 v99, 1.0, v99
	v_add_f32_e32 v100, 1.0, v100
	v_add_f32_e32 v101, 1.0, v101
	v_add_f32_e32 v102, 1.0, v102
	v_add_f32_e32 v103, 1.0, v103
	v_log_f32_e32 v96, v96
	v_log_f32_e32 v97, v97
	v_log_f32_e32 v98, v98
	v_log_f32_e32 v99, v99
	v_log_f32_e32 v100, v100
	v_log_f32_e32 v101, v101
	v_log_f32_e32 v102, v102
	v_log_f32_e32 v103, v103
	v_max_f32_e32 v60, 0, v60
	v_max_f32_e32 v62, 0, v62
	v_max_f32_e32 v64, 0, v64
	v_max_f32_e32 v66, 0, v66
	v_max_f32_e32 v68, 0, v68
	v_max_f32_e32 v70, 0, v70
	v_max_f32_e32 v72, 0, v72
	v_max_f32_e32 v74, 0, v74
	v_mul_f32_e32 v104, 0x3f317217, v96
	v_mul_f32_e32 v105, 0x3f317217, v97
	v_mul_f32_e32 v106, 0x3f317217, v98
	v_mul_f32_e32 v107, 0x3f317217, v99
	v_mul_f32_e32 v108, 0x3f317217, v100
	v_mul_f32_e32 v109, 0x3f317217, v101
	v_mul_f32_e32 v110, 0x3f317217, v102
	v_mul_f32_e32 v111, 0x3f317217, v103
	v_fma_f32 v104, v96, s75, -v104
	v_fma_f32 v105, v97, s75, -v105
	v_fma_f32 v106, v98, s75, -v106
	v_fma_f32 v107, v99, s75, -v107
	v_fma_f32 v108, v100, s75, -v108
	v_fma_f32 v109, v101, s75, -v109
	v_fma_f32 v110, v102, s75, -v110
	v_fma_f32 v111, v103, s75, -v111
	v_fmac_f32_e32 v104, 0x3377d1cf, v96
	v_fmac_f32_e32 v105, 0x3377d1cf, v97
	v_fmac_f32_e32 v106, 0x3377d1cf, v98
	v_fmac_f32_e32 v107, 0x3377d1cf, v99
	v_fmac_f32_e32 v108, 0x3377d1cf, v100
	v_fmac_f32_e32 v109, 0x3377d1cf, v101
	v_fmac_f32_e32 v110, 0x3377d1cf, v102
	v_fmac_f32_e32 v111, 0x3377d1cf, v103
	v_fmac_f32_e32 v104, 0x3f317217, v96
	v_fmac_f32_e32 v105, 0x3f317217, v97
	v_fmac_f32_e32 v106, 0x3f317217, v98
	v_fmac_f32_e32 v107, 0x3f317217, v99
	v_fmac_f32_e32 v108, 0x3f317217, v100
	v_fmac_f32_e32 v109, 0x3f317217, v101
	v_fmac_f32_e32 v110, 0x3f317217, v102
	v_fmac_f32_e32 v111, 0x3f317217, v103
	v_add_f32_e32 v60, v60, v104
	v_add_f32_e32 v62, v62, v105
	v_add_f32_e32 v64, v64, v106
	v_add_f32_e32 v66, v66, v107
	v_add_f32_e32 v68, v68, v108
	v_add_f32_e32 v70, v70, v109
	v_add_f32_e32 v72, v72, v110
	v_add_f32_e32 v74, v74, v111
	v_cndmask_b32_e32 v60, 0, v60, vcc
	v_cndmask_b32_e64 v62, 0, v62, s[14:15]
	v_cndmask_b32_e64 v64, 0, v64, s[16:17]
	v_cndmask_b32_e64 v66, 0, v66, s[18:19]
	v_cndmask_b32_e64 v68, 0, v68, s[20:21]
	v_cndmask_b32_e64 v70, 0, v70, s[22:23]
	v_cndmask_b32_e64 v72, 0, v72, s[24:25]
	v_cndmask_b32_e64 v74, 0, v74, s[26:27]
	v_add_f32_e32 v58, 0, v60
	v_add_f32_e32 v58, v58, v62
	v_add_f32_e32 v58, v58, v64
	v_add_f32_e32 v58, v58, v66
	v_add_f32_e32 v58, v58, v68
	v_add_f32_e32 v58, v58, v70
	v_add_f32_e32 v58, v58, v72
	v_add_f32_e32 v58, v58, v74
	ds_bpermute_b32 v61, v78, v58
	v_mov_b32_e32 v73, v74
	v_mov_b32_e32 v71, v72
	v_mov_b32_e32 v69, v70
	v_mov_b32_e32 v67, v68
	s_waitcnt lgkmcnt(0)
	v_add_f32_e32 v61, v58, v61
	v_cndmask_b32_e64 v61, v61, v58, s[8:9]
	ds_bpermute_b32 v63, v79, v61
	v_mov_b32_e32 v65, v66
	s_bitcmp1_b32 exec_hi, 0
	s_waitcnt lgkmcnt(0)
	v_add_f32_e32 v63, v61, v63
	v_cndmask_b32_e64 v61, v61, v63, s[10:11]
	ds_bpermute_b32 v63, v80, v61
	s_waitcnt lgkmcnt(0)
	v_add_f32_e32 v63, v61, v63
	v_cndmask_b32_e64 v94, v61, v63, s[12:13]
	v_sub_f32_e32 v75, v94, v58
	v_mov_b32_e32 v58, v39
	v_pk_add_f32 v[92:93], v[58:59], v[74:75] neg_lo:[0,1] neg_hi:[0,1]
	v_mov_b32_e32 v63, v64
	v_add_f32_e32 v39, v92, v93
	v_mul_f32_e32 v39, 0x3fb8aa3b, v39
	v_exp_f32_e32 v39, v39
	v_mov_b32_e32 v61, v62
	v_cndmask_b32_e64 v58, 0, v39, s[26:27]
	v_mov_b32_e32 v39, v93
	v_pk_add_f32 v[38:39], v[38:39], v[72:73] neg_lo:[0,1] neg_hi:[0,1]
	s_nop 0
	v_add_f32_e32 v38, v38, v39
	v_mul_f32_e32 v38, 0x3fb8aa3b, v38
	v_exp_f32_e32 v38, v38
	s_nop 0
	v_cndmask_b32_e64 v73, 0, v38, s[24:25]
	v_mov_b32_e32 v38, v37
	v_pk_add_f32 v[38:39], v[38:39], v[70:71] neg_lo:[0,1] neg_hi:[0,1]
	s_nop 0
	v_add_f32_e32 v37, v38, v39
	v_mul_f32_e32 v37, 0x3fb8aa3b, v37
	v_exp_f32_e32 v37, v37
	s_nop 0
	v_cndmask_b32_e64 v38, 0, v37, s[22:23]
	v_mov_b32_e32 v37, v39
	v_pk_add_f32 v[36:37], v[36:37], v[68:69] neg_lo:[0,1] neg_hi:[0,1]
	s_nop 0
	v_add_f32_e32 v36, v36, v37
	v_mul_f32_e32 v36, 0x3fb8aa3b, v36
	v_exp_f32_e32 v36, v36
	s_nop 0
	v_cndmask_b32_e64 v39, 0, v36, s[20:21]
	v_mov_b32_e32 v36, v35
	v_pk_add_f32 v[36:37], v[36:37], v[66:67] neg_lo:[0,1] neg_hi:[0,1]
	s_nop 0
	v_add_f32_e32 v35, v36, v37
	v_mul_f32_e32 v35, 0x3fb8aa3b, v35
	v_exp_f32_e32 v35, v35
	s_nop 0
	v_cndmask_b32_e64 v36, 0, v35, s[18:19]
	v_mov_b32_e32 v35, v37
	v_pk_add_f32 v[34:35], v[34:35], v[64:65] neg_lo:[0,1] neg_hi:[0,1]
	s_nop 0
	v_add_f32_e32 v34, v34, v35
	v_mul_f32_e32 v34, 0x3fb8aa3b, v34
	v_exp_f32_e32 v34, v34
	s_nop 0
	v_cndmask_b32_e64 v37, 0, v34, s[16:17]
	v_mov_b32_e32 v34, v33
	v_pk_add_f32 v[34:35], v[34:35], v[62:63] neg_lo:[0,1] neg_hi:[0,1]
	s_nop 0
	v_add_f32_e32 v33, v34, v35
	v_mul_f32_e32 v33, 0x3fb8aa3b, v33
	v_exp_f32_e32 v33, v33
	s_nop 0
	v_cndmask_b32_e64 v34, 0, v33, s[14:15]
	v_mov_b32_e32 v33, v35
	v_pk_add_f32 v[32:33], v[32:33], v[60:61] neg_lo:[0,1] neg_hi:[0,1]
	v_cvt_pk_bf16_f32 v35, v73, v58
	v_add_f32_e32 v32, v32, v33
	v_mul_f32_e32 v32, 0x3fb8aa3b, v32
	v_exp_f32_e32 v32, v32
	v_cvt_pk_bf16_f32 v33, v37, v36
	ds_bpermute_b32 v60, v53, v94
	s_mov_b32 s14, 0xc2f00000
	v_cndmask_b32_e32 v32, 0, v32, vcc
	v_cvt_pk_bf16_f32 v32, v32, v34
	v_cvt_pk_bf16_f32 v34, v39, v38
	ds_write_b128 v55, v[32:35]
	s_waitcnt lgkmcnt(0)
	s_barrier
; __device__ __forceinline__ void attn_phase(const Params& p, char* shmc, int tid, int wv) {
;     ...
;       {
;         const int ntb = (wv >> 2) * 4;
; #pragma unroll
;         for (int kk = 0; kk < 2; ++kk) {
;           const bf16x8 a = *(const bf16x8*)&Ps[(16 * mt + r) * 72 + kk * 32 + quad * 8];
; #pragma unroll
;           for (int i = 0; i < 4; ++i) {
;             const bf16x8 b = *(const bf16x8*)&Vt[(16 * (ntb + i) + r) * 72 + kk * 32 + quad * 8];
;             oacc[i] = __builtin_amdgcn_mfma_f32_16x16x32_bf16(a, b, oacc[i], 0, 0, 0);
;           }
;         }
;       }
;       const int more = __syncthreads_or(carry > -120.f);
;       if (!more) break;
	ds_read_b128 v[96:99], v76
	ds_read_b128 v[104:107], v86 offset:34816
	ds_read_b128 v[108:111], v87 offset:34816
	ds_read_b128 v[112:115], v88 offset:34816
	ds_read_b128 v[116:119], v89 offset:34816
	ds_read_b128 v[100:103], v76 offset:64
	ds_read_b128 v[120:123], v86 offset:34880
	ds_read_b128 v[124:127], v87 offset:34880
	ds_read_b128 v[128:131], v88 offset:34880
	ds_read_b128 v[132:135], v89 offset:34880
	v_sub_f32_e32 v59, v59, v60
	v_cmp_lt_f32_e32 vcc, s14, v59
	s_waitcnt lgkmcnt(8)
	v_mfma_f32_16x16x32_bf16 v[16:19], v[96:99], v[104:107], v[16:19]
	s_waitcnt lgkmcnt(7)
	v_mfma_f32_16x16x32_bf16 v[20:23], v[96:99], v[108:111], v[20:23]
	s_waitcnt lgkmcnt(6)
	v_mfma_f32_16x16x32_bf16 v[24:27], v[96:99], v[112:115], v[24:27]
	s_waitcnt lgkmcnt(5)
	v_mfma_f32_16x16x32_bf16 v[28:31], v[96:99], v[116:119], v[28:31]
	s_waitcnt lgkmcnt(3)
	v_mfma_f32_16x16x32_bf16 v[16:19], v[100:103], v[120:123], v[16:19]
	s_waitcnt lgkmcnt(2)
	v_mfma_f32_16x16x32_bf16 v[20:23], v[100:103], v[124:127], v[20:23]
	s_waitcnt lgkmcnt(1)
	v_mfma_f32_16x16x32_bf16 v[24:27], v[100:103], v[128:131], v[24:27]
	s_waitcnt lgkmcnt(0)
	v_mfma_f32_16x16x32_bf16 v[28:31], v[100:103], v[132:135], v[28:31]
	s_cmp_lg_u64 vcc, 0
	s_cselect_b32 s16, 1, 0
	v_mov_b32_e32 v32, s16
	s_andn2_b64 vcc, exec, s[94:95]
	s_cbranch_vccnz .Lat_310B
	s_and_saveexec_b64 s[14:15], s[4:5]
	v_mov_b32_e32 v32, s16
	ds_write_b32 v213, v32
	s_or_b64 exec, exec, s[14:15]
	s_waitcnt lgkmcnt(0)
	s_barrier
	s_and_saveexec_b64 s[14:15], s[98:99]
	s_cbranch_execz .Lat_309B
	v_mbcnt_lo_u32_b32 v32, exec_lo, 0
	v_mbcnt_hi_u32_b32 v32, exec_hi, v32
	v_cmp_eq_u32_e32 vcc, 0, v32
	s_and_b64 exec, exec, vcc
	s_cbranch_execz .Lat_309B
	v_mov_b32_e32 v32, s16
	ds_or_b32 v213, v32
	s_branch .Lat_309B

; #define OLOAD(nn_, QF, PF) do { const long nn = (nn_) < 256 ? (nn_) : 255; \
;       _Pragma("unroll") for (int f = 0; f < 16; ++f) QF[f] = ldg16(qb_ + nn * qst + (long)f * qfs); \
;       _Pragma("unroll") for (int f = 0; f < 8; ++f) PF[f] = ldg16(pb_ + nn * 8192 + f * 1024); } while (0)
; #define OBAR do { asm volatile("s_waitcnt lgkmcnt(0)" ::: "memory"); __builtin_amdgcn_s_barrier(); } while (0)
; __device__ __forceinline__ void scan_phase(const Params& p, char* shmc, int tid, int wv) {
;     ...
;     const int po = wv & 1;
;     OLOAD(po, qe_, pe_);
;     OLOAD(po + 2, qo_, po_);
;     __builtin_amdgcn_s_barrier();
;     if (po) OBAR;
;     for (int c0 = po; c0 < 256; c0 += 4) {
;       OSTEP(c0, qe_, pe_);     OLOAD(c0 + 4, qe_, pe_);
;       OBAR;
;       OSTEP(c0 + 2, qo_, po_); OLOAD(c0 + 6, qo_, po_);
;       if (!(po && c0 + 4 >= 256)) OBAR;
;     }
.LBB0_369:
	v_mov_b32_e32 v64, s33
	ds_read_b32 v64, v64
	s_waitcnt lgkmcnt(0)
	v_cmp_lt_u32_e32 vcc, s7, v64
	s_or_b64 s[18:19], vcc, s[18:19]
	s_andn2_b64 exec, exec, s[18:19]
	s_cbranch_execnz .LBB0_369
	s_or_b64 exec, exec, s[18:19]
	v_add_u32_e32 v247, 0x20c00, v245
	s_lshl_b32 s22, s7, 17
	v_mfma_f32_16x16x32_bf16 v[4:7], v[4:7], v[196:199], v[24:27]
	v_mfma_f32_16x16x32_bf16 v[24:27], v[48:51], v[196:199], v[40:43]
	v_mfma_f32_16x16x32_bf16 v[16:19], v[16:19], v[196:199], v[28:31]
	v_mfma_f32_16x16x32_bf16 v[28:31], v[68:71], v[196:199], v[60:63]
	s_nop 0
	ds_read_b128 v[40:43], v247
	ds_read_b128 v[48:51], v247 offset:1024
	s_waitcnt lgkmcnt(1)
	v_mfma_f32_16x16x32_bf16 v[4:7], v[56:59], v[40:43], v[4:7]
	v_mfma_f32_16x16x32_bf16 v[16:19], v[44:47], v[40:43], v[16:19]
	v_mfma_f32_16x16x32_bf16 v[24:27], v[36:39], v[40:43], v[24:27]
	v_mfma_f32_16x16x32_bf16 v[12:15], v[12:15], v[40:43], v[28:31]
	s_waitcnt lgkmcnt(0)
	v_mfma_f32_16x16x32_bf16 v[4:7], v[52:55], v[48:51], v[4:7]
	v_mfma_f32_16x16x32_bf16 v[16:19], v[32:35], v[48:51], v[16:19]
	v_mfma_f32_16x16x32_bf16 v[24:27], v[20:23], v[48:51], v[24:27]
	v_mfma_f32_16x16x32_bf16 v[8:11], v[8:11], v[48:51], v[12:15]
	s_barrier
	v_or_b32_e32 v56, s22, v241
	v_lshlrev_b32_e32 v212, 1, v56
	v_lshl_add_u64 v[56:57], v[0:1], 0, v[212:213]
	s_mov_b32 s21, 0
	s_nop 7
	v_cvt_pk_bf16_f32 v60, v4, s0
	global_store_short v[56:57], v60, off
	v_cvt_pk_bf16_f32 v61, v5, s0
	s_mov_b32 s20, 0x1000
	v_lshl_add_u64 v[66:67], v[56:57], 0, s[20:21]
	global_store_short v[66:67], v61, off
	v_cvt_pk_bf16_f32 v64, v6, s0
	s_mov_b32 s20, 0x2000
	v_lshl_add_u64 v[72:73], v[56:57], 0, s[20:21]
	global_store_short v[72:73], v64, off
	v_cvt_pk_bf16_f32 v65, v7, s0
	s_mov_b32 s20, 0x3000
	v_lshl_add_u64 v[74:75], v[56:57], 0, s[20:21]
	global_store_short v[74:75], v65, off
	v_cvt_pk_bf16_f32 v60, v16, s0
	s_mov_b32 s20, 0x10000
	v_lshl_add_u64 v[62:63], v[56:57], 0, s[20:21]
	global_store_short v[62:63], v60, off
	v_cvt_pk_bf16_f32 v61, v17, s0
	s_mov_b32 s20, 0x11000
	v_lshl_add_u64 v[66:67], v[56:57], 0, s[20:21]
	global_store_short v[66:67], v61, off
	v_cvt_pk_bf16_f32 v64, v18, s0
	s_mov_b32 s20, 0x12000
	v_lshl_add_u64 v[72:73], v[56:57], 0, s[20:21]
	global_store_short v[72:73], v64, off
	v_cvt_pk_bf16_f32 v65, v19, s0
	s_mov_b32 s20, 0x13000
	v_lshl_add_u64 v[74:75], v[56:57], 0, s[20:21]
	global_store_short v[74:75], v65, off
	v_cvt_pk_bf16_f32 v60, v24, s0
	s_mov_b32 s20, 0x20000
	v_lshl_add_u64 v[62:63], v[56:57], 0, s[20:21]
	global_store_short v[62:63], v60, off
	v_cvt_pk_bf16_f32 v61, v25, s0
	s_mov_b32 s20, 0x21000
	v_lshl_add_u64 v[66:67], v[56:57], 0, s[20:21]
	global_store_short v[66:67], v61, off
	v_cvt_pk_bf16_f32 v64, v26, s0
	s_mov_b32 s20, 0x22000
	v_lshl_add_u64 v[72:73], v[56:57], 0, s[20:21]
	global_store_short v[72:73], v64, off
	v_cvt_pk_bf16_f32 v65, v27, s0
	s_mov_b32 s20, 0x23000
	v_lshl_add_u64 v[74:75], v[56:57], 0, s[20:21]
	global_store_short v[74:75], v65, off
	v_cvt_pk_bf16_f32 v60, v8, s0
	s_mov_b32 s20, 0x30000
	v_lshl_add_u64 v[62:63], v[56:57], 0, s[20:21]
	global_store_short v[62:63], v60, off
	v_cvt_pk_bf16_f32 v61, v9, s0
	s_mov_b32 s20, 0x31000
	v_lshl_add_u64 v[66:67], v[56:57], 0, s[20:21]
	global_store_short v[66:67], v61, off
	v_cvt_pk_bf16_f32 v64, v10, s0
	s_mov_b32 s20, 0x32000
	v_lshl_add_u64 v[72:73], v[56:57], 0, s[20:21]
	global_store_short v[72:73], v64, off
	v_cvt_pk_bf16_f32 v65, v11, s0
	s_mov_b32 s20, 0x33000
	v_lshl_add_u64 v[74:75], v[56:57], 0, s[20:21]
	global_store_short v[74:75], v65, off
	s_add_i32 s15, s7, 4
	s_cmpk_gt_u32 s7, 0xfb
	s_cselect_b64 s[18:19], -1, 0
	s_cmpk_lt_u32 s7, 0xfc
	s_cselect_b32 s88, s15, 0xff
	v_mov_b32_e32 v4, s88
	v_mad_u64_u32 v[4:5], s[20:21], s12, v4, v[226:227]
	v_lshl_add_u64 v[6:7], v[4:5], 0, s[16:17]
	global_load_dwordx4 v[24:27], v[4:5], off
	global_load_dwordx4 v[28:31], v[6:7], off
	v_lshl_add_u64 v[4:5], v[6:7], 0, s[16:17]
	v_lshl_add_u64 v[8:9], v[4:5], 0, s[16:17]
	global_load_dwordx4 v[40:43], v[4:5], off
	s_nop 0
	global_load_dwordx4 v[4:7], v[8:9], off
	v_lshl_add_u64 v[8:9], v[8:9], 0, s[16:17]
	v_lshl_add_u64 v[10:11], v[8:9], 0, s[16:17]
	global_load_dwordx4 v[60:63], v[8:9], off
	global_load_dwordx4 v[64:67], v[10:11], off
	v_lshl_add_u64 v[8:9], v[10:11], 0, s[16:17]
	v_lshl_add_u64 v[10:11], v[8:9], 0, s[16:17]
	global_load_dwordx4 v[72:75], v[8:9], off
	global_load_dwordx4 v[16:19], v[10:11], off
	v_lshl_add_u64 v[8:9], v[10:11], 0, s[16:17]
	global_load_dwordx4 v[80:83], v[8:9], off
	v_lshl_add_u64 v[8:9], v[8:9], 0, s[16:17]
	global_load_dwordx4 v[84:87], v[8:9], off
	v_lshl_add_u64 v[8:9], v[8:9], 0, s[16:17]
	global_load_dwordx4 v[92:95], v[8:9], off
	v_lshl_add_u64 v[8:9], v[8:9], 0, s[16:17]
	global_load_dwordx4 v[48:51], v[8:9], off
	v_lshl_add_u64 v[8:9], v[8:9], 0, s[16:17]
	global_load_dwordx4 v[100:103], v[8:9], off
	v_lshl_add_u64 v[8:9], v[8:9], 0, s[16:17]
	global_load_dwordx4 v[108:111], v[8:9], off
	v_lshl_add_u64 v[8:9], v[8:9], 0, s[16:17]
	global_load_dwordx4 v[116:119], v[8:9], off
	v_lshl_add_u64 v[8:9], v[8:9], 0, s[16:17]
	s_lshl_b64 s[20:21], s[88:89], 13
	global_load_dwordx4 v[68:71], v[8:9], off
	v_lshl_add_u64 v[8:9], v[228:229], 0, s[20:21]
	global_load_dwordx4 v[56:59], v[8:9], off
	global_load_dwordx4 v[52:55], v[8:9], off offset:1024
	global_load_dwordx4 v[44:47], v[8:9], off offset:2048
	global_load_dwordx4 v[32:35], v[8:9], off offset:3072
	v_add_co_u32_e32 v8, vcc, s66, v8
	s_add_i32 s23, s7, 3
	s_nop 0
	v_addc_co_u32_e32 v9, vcc, 0, v9, vcc
	global_load_dwordx4 v[36:39], v[8:9], off
	global_load_dwordx4 v[20:23], v[8:9], off offset:1024
	global_load_dwordx4 v[12:15], v[8:9], off offset:2048
	s_nop 0
	global_load_dwordx4 v[8:11], v[8:9], off offset:3072
	s_waitcnt lgkmcnt(0)
	s_barrier
	ds_read_b128 v[204:207], v246
	ds_read_b128 v[208:211], v246 offset:1024
	ds_read_b128 v[200:203], v246 offset:2048
	ds_read_b128 v[196:199], v246 offset:3072
	s_waitcnt lgkmcnt(0)
	s_and_saveexec_b64 s[20:21], s[10:11]
	s_cbranch_execz .LBB0_372
	s_add_i32 s24, s35, 0x110
	v_mov_b32_e32 v232, s24
	v_mov_b32_e32 v212, s23
	ds_write_b32 v232, v212

; #define OLOAD(nn_, QF, PF) do { const long nn = (nn_) < 256 ? (nn_) : 255; \
;       _Pragma("unroll") for (int f = 0; f < 16; ++f) QF[f] = ldg16(qb_ + nn * qst + (long)f * qfs); \
;       _Pragma("unroll") for (int f = 0; f < 8; ++f) PF[f] = ldg16(pb_ + nn * 8192 + f * 1024); } while (0)
; #define OBAR do { asm volatile("s_waitcnt lgkmcnt(0)" ::: "memory"); __builtin_amdgcn_s_barrier(); } while (0)
; __device__ __forceinline__ void scan_phase(const Params& p, char* shmc, int tid, int wv) {
;     ...
;     const int po = wv & 1;
;     OLOAD(po, qe_, pe_);
;     OLOAD(po + 2, qo_, po_);
;     __builtin_amdgcn_s_barrier();
;     if (po) OBAR;
;     for (int c0 = po; c0 < 256; c0 += 4) {
;       OSTEP(c0, qe_, pe_);     OLOAD(c0 + 4, qe_, pe_);
;       OBAR;
;       OSTEP(c0 + 2, qo_, po_); OLOAD(c0 + 6, qo_, po_);
;       if (!(po && c0 + 4 >= 256)) OBAR;
;     }
.LBB0_373:
	v_mov_b32_e32 v156, s33
	ds_read_b32 v156, v156
	s_waitcnt lgkmcnt(0)
	v_cmp_le_u32_e32 vcc, s23, v156
	s_or_b64 s[20:21], vcc, s[20:21]
	s_andn2_b64 exec, exec, s[20:21]
	s_cbranch_execnz .LBB0_373
	s_or_b64 exec, exec, s[20:21]
	v_add_lshl_u32 v212, v244, s22, 1
	v_readlane_b32 s22, v253, 33
	v_readlane_b32 s23, v253, 34
	v_mfma_f32_16x16x32_bf16 v[76:79], v[76:79], v[196:199], v[124:127]
	v_mfma_f32_16x16x32_bf16 v[104:107], v[104:107], v[196:199], v[144:147]
	v_mfma_f32_16x16x32_bf16 v[124:127], v[148:151], v[196:199], v[152:155]
	v_mfma_f32_16x16x32_bf16 v[120:123], v[132:135], v[196:199], v[120:123]
	s_nop 0
	ds_read_b128 v[144:147], v247
	ds_read_b128 v[148:151], v247 offset:1024
	s_waitcnt lgkmcnt(1)
	v_mfma_f32_16x16x32_bf16 v[76:79], v[168:171], v[144:147], v[76:79]
	v_mfma_f32_16x16x32_bf16 v[104:107], v[136:139], v[144:147], v[104:107]
	v_mfma_f32_16x16x32_bf16 v[124:127], v[140:143], v[144:147], v[124:127]
	v_mfma_f32_16x16x32_bf16 v[96:99], v[96:99], v[144:147], v[120:123]
	s_waitcnt lgkmcnt(0)
	v_mfma_f32_16x16x32_bf16 v[76:79], v[160:163], v[148:151], v[76:79]
	v_mfma_f32_16x16x32_bf16 v[104:107], v[128:131], v[148:151], v[104:107]
	v_mfma_f32_16x16x32_bf16 v[124:127], v[112:115], v[148:151], v[124:127]
	v_mfma_f32_16x16x32_bf16 v[96:99], v[88:91], v[148:151], v[96:99]
	s_barrier
	v_lshl_add_u64 v[152:153], v[0:1], 0, v[212:213]
	s_mov_b32 s25, 0
	s_nop 7
	v_cvt_pk_bf16_f32 v154, v76, s0
	global_store_short v[152:153], v154, off
	v_cvt_pk_bf16_f32 v155, v77, s0
	s_mov_b32 s24, 0x1000
	v_lshl_add_u64 v[164:165], v[152:153], 0, s[24:25]
	global_store_short v[164:165], v155, off
	v_cvt_pk_bf16_f32 v156, v78, s0
	s_mov_b32 s24, 0x2000
	v_lshl_add_u64 v[166:167], v[152:153], 0, s[24:25]
	global_store_short v[166:167], v156, off
	v_cvt_pk_bf16_f32 v157, v79, s0
	s_mov_b32 s24, 0x3000
	v_lshl_add_u64 v[172:173], v[152:153], 0, s[24:25]
	global_store_short v[172:173], v157, off
	v_cvt_pk_bf16_f32 v154, v104, s0
	s_mov_b32 s24, 0x10000
	v_lshl_add_u64 v[158:159], v[152:153], 0, s[24:25]
	global_store_short v[158:159], v154, off
	v_cvt_pk_bf16_f32 v155, v105, s0
	s_mov_b32 s24, 0x11000
	v_lshl_add_u64 v[164:165], v[152:153], 0, s[24:25]
	global_store_short v[164:165], v155, off
	v_cvt_pk_bf16_f32 v156, v106, s0
	s_mov_b32 s24, 0x12000
	v_lshl_add_u64 v[166:167], v[152:153], 0, s[24:25]
	global_store_short v[166:167], v156, off
	v_cvt_pk_bf16_f32 v157, v107, s0
	s_mov_b32 s24, 0x13000
	v_lshl_add_u64 v[172:173], v[152:153], 0, s[24:25]
	global_store_short v[172:173], v157, off
	v_cvt_pk_bf16_f32 v154, v124, s0
	s_mov_b32 s24, 0x20000
	v_lshl_add_u64 v[158:159], v[152:153], 0, s[24:25]
	global_store_short v[158:159], v154, off
	v_cvt_pk_bf16_f32 v155, v125, s0
	s_mov_b32 s24, 0x21000
	v_lshl_add_u64 v[164:165], v[152:153], 0, s[24:25]
	global_store_short v[164:165], v155, off
	v_cvt_pk_bf16_f32 v156, v126, s0
	s_mov_b32 s24, 0x22000
	v_lshl_add_u64 v[166:167], v[152:153], 0, s[24:25]
	global_store_short v[166:167], v156, off
	v_cvt_pk_bf16_f32 v157, v127, s0
	s_mov_b32 s24, 0x23000
	v_lshl_add_u64 v[172:173], v[152:153], 0, s[24:25]
	global_store_short v[172:173], v157, off
	v_cvt_pk_bf16_f32 v154, v96, s0
	s_mov_b32 s24, 0x30000
	v_lshl_add_u64 v[158:159], v[152:153], 0, s[24:25]
	global_store_short v[158:159], v154, off
	v_cvt_pk_bf16_f32 v155, v97, s0
	s_mov_b32 s24, 0x31000
	v_lshl_add_u64 v[164:165], v[152:153], 0, s[24:25]
	global_store_short v[164:165], v155, off
	v_cvt_pk_bf16_f32 v156, v98, s0
	s_mov_b32 s24, 0x32000
	v_lshl_add_u64 v[166:167], v[152:153], 0, s[24:25]
	global_store_short v[166:167], v156, off
	v_cvt_pk_bf16_f32 v157, v99, s0
	s_mov_b32 s24, 0x33000
	v_lshl_add_u64 v[172:173], v[152:153], 0, s[24:25]
	global_store_short v[172:173], v157, off
	s_min_u32 s20, s7, 0xf9
	s_add_i32 s20, s20, 6
	s_mul_i32 s88, s12, s20
	v_lshl_add_u64 v[76:77], v[226:227], 0, s[88:89]
	v_lshl_add_u64 v[78:79], v[76:77], 0, s[16:17]
	global_load_dwordx4 v[120:123], v[76:77], off
	global_load_dwordx4 v[124:127], v[78:79], off
	v_lshl_add_u64 v[76:77], v[78:79], 0, s[16:17]
	v_lshl_add_u64 v[88:89], v[76:77], 0, s[16:17]
	global_load_dwordx4 v[144:147], v[76:77], off
	s_nop 0
	global_load_dwordx4 v[76:79], v[88:89], off
	v_lshl_add_u64 v[88:89], v[88:89], 0, s[16:17]
	v_lshl_add_u64 v[90:91], v[88:89], 0, s[16:17]
	global_load_dwordx4 v[152:155], v[88:89], off
	global_load_dwordx4 v[156:159], v[90:91], off
	v_lshl_add_u64 v[88:89], v[90:91], 0, s[16:17]
	v_lshl_add_u64 v[90:91], v[88:89], 0, s[16:17]
	global_load_dwordx4 v[164:167], v[88:89], off
	global_load_dwordx4 v[104:107], v[90:91], off
	v_lshl_add_u64 v[88:89], v[90:91], 0, s[16:17]
	global_load_dwordx4 v[172:175], v[88:89], off
	v_lshl_add_u64 v[88:89], v[88:89], 0, s[16:17]
	global_load_dwordx4 v[176:179], v[88:89], off
	v_lshl_add_u64 v[88:89], v[88:89], 0, s[16:17]
	global_load_dwordx4 v[180:183], v[88:89], off
	v_lshl_add_u64 v[88:89], v[88:89], 0, s[16:17]
	global_load_dwordx4 v[148:151], v[88:89], off
	v_lshl_add_u64 v[88:89], v[88:89], 0, s[16:17]
	global_load_dwordx4 v[184:187], v[88:89], off
	v_lshl_add_u64 v[88:89], v[88:89], 0, s[16:17]
	global_load_dwordx4 v[188:191], v[88:89], off
	v_lshl_add_u64 v[88:89], v[88:89], 0, s[16:17]
	global_load_dwordx4 v[192:195], v[88:89], off
	v_lshl_add_u64 v[88:89], v[88:89], 0, s[16:17]
	s_lshl_b32 s88, s20, 13
	global_load_dwordx4 v[132:135], v[88:89], off
	v_lshl_add_u64 v[88:89], v[228:229], 0, s[88:89]
	global_load_dwordx4 v[168:171], v[88:89], off
	global_load_dwordx4 v[160:163], v[88:89], off offset:1024
	global_load_dwordx4 v[136:139], v[88:89], off offset:2048
	global_load_dwordx4 v[128:131], v[88:89], off offset:3072
	v_add_co_u32_e32 v88, vcc, 0x1000, v88
	s_cmpk_gt_u32 s7, 0xfb
	s_nop 0
	v_addc_co_u32_e32 v89, vcc, 0, v89, vcc
	global_load_dwordx4 v[140:143], v[88:89], off
	global_load_dwordx4 v[112:115], v[88:89], off offset:1024
	global_load_dwordx4 v[96:99], v[88:89], off offset:2048
	s_nop 0
	global_load_dwordx4 v[88:91], v[88:89], off offset:3072
	s_cselect_b64 s[20:21], -1, 0
	s_and_b64 s[20:21], s[22:23], s[20:21]
	s_and_b64 vcc, exec, s[20:21]
	s_cbranch_vccnz .LBB0_365
	s_waitcnt lgkmcnt(0)
	s_barrier
	s_branch .LBB0_365
